# first grid barrier: the sixteen census counter loads issued together and waited for once instead of one dependent round trip each
# baseline (speedup 1.0000x reference)
.LBB0_678:
	v_readlane_b32 s4, v254, 30
	v_readlane_b32 s5, v254, 31
	v_readlane_b32 s6, v255, 3
	s_waitcnt lgkmcnt(0)
	s_nop 4
	global_load_dword v0, v41, s[4:5] sc1
	v_readlane_b32 s4, v254, 32
	v_readlane_b32 s5, v254, 33
	s_nop 4
	global_load_dword v1, v41, s[4:5] sc1
	v_readlane_b32 s4, v254, 34
	v_readlane_b32 s5, v254, 35
	s_nop 4
	global_load_dword v2, v41, s[4:5] sc1
	v_readlane_b32 s4, v254, 36
	v_readlane_b32 s5, v254, 37
	s_nop 4
	global_load_dword v3, v41, s[4:5] sc1
	v_readlane_b32 s4, v254, 38
	v_readlane_b32 s5, v254, 39
	s_nop 4
	global_load_dword v4, v41, s[4:5] sc1
	v_readlane_b32 s4, v254, 40
	v_readlane_b32 s5, v254, 41
	s_nop 4
	global_load_dword v5, v41, s[4:5] sc1
	v_readlane_b32 s4, v254, 42
	v_readlane_b32 s5, v254, 43
	s_nop 4
	global_load_dword v6, v41, s[4:5] sc1
	v_readlane_b32 s4, v254, 44
	v_readlane_b32 s5, v254, 45
	s_nop 4
	global_load_dword v7, v41, s[4:5] sc1
	v_readlane_b32 s4, v254, 46
	v_readlane_b32 s5, v254, 47
	s_nop 4
	global_load_dword v8, v41, s[4:5] sc1
	v_readlane_b32 s4, v254, 48
	v_readlane_b32 s5, v254, 49
	s_nop 4
	global_load_dword v9, v41, s[4:5] sc1
	v_readlane_b32 s4, v254, 50
	v_readlane_b32 s5, v254, 51
	s_nop 4
	global_load_dword v10, v41, s[4:5] sc1
	v_readlane_b32 s4, v254, 52
	v_readlane_b32 s5, v254, 53
	s_nop 4
	global_load_dword v11, v41, s[4:5] sc1
	v_readlane_b32 s4, v254, 54
	v_readlane_b32 s5, v254, 55
	s_nop 4
	global_load_dword v12, v41, s[4:5] sc1
	v_readlane_b32 s4, v254, 56
	v_readlane_b32 s5, v254, 57
	s_nop 4
	global_load_dword v13, v41, s[4:5] sc1
	v_readlane_b32 s4, v254, 58
	v_readlane_b32 s5, v254, 59
	s_nop 4
	global_load_dword v14, v41, s[4:5] sc1
	v_readlane_b32 s4, v254, 60
	v_readlane_b32 s5, v254, 61
	s_nop 4
	global_load_dword v15, v41, s[4:5] sc1
	s_mov_b64 s[4:5], -1
	s_waitcnt vmcnt(0)
	v_add_u32_e32 v16, v1, v0
	v_add_u32_e32 v16, v16, v2
	v_add_u32_e32 v16, v16, v3
	v_add_u32_e32 v16, v16, v4
	v_add_u32_e32 v16, v16, v5
	v_add_u32_e32 v16, v16, v6
	v_add_u32_e32 v16, v16, v7
	v_add_u32_e32 v16, v16, v8
	v_add_u32_e32 v16, v16, v9
	v_add_u32_e32 v16, v16, v10
	v_add_u32_e32 v16, v16, v11
	v_add_u32_e32 v16, v16, v12
	v_add_u32_e32 v16, v16, v13
	v_add_u32_e32 v16, v16, v14
	v_add_u32_e32 v16, v16, v15
	v_cmp_eq_u32_e32 vcc, s6, v16
	s_mov_b64 s[6:7], -1
	s_cbranch_vccnz .LBB0_677
	s_and_b32 s4, s10, 0xff
	s_cmp_eq_u32 s4, 0
	s_mov_b64 s[4:5], -1
	s_mov_b64 s[8:9], -1
	s_sleep 1
	s_cbranch_scc0 .LBB0_682
	v_readlane_b32 s4, v254, 28
	v_readlane_b32 s5, v254, 29
	s_nop 4
	global_load_dword v16, v41, s[4:5] sc1
	s_waitcnt vmcnt(0)
	v_cmp_eq_u32_e32 vcc, 0, v16
	s_cbranch_vccnz .LBB0_684
	s_mov_b64 s[8:9], 0
	s_mov_b64 s[4:5], -1
